# HGRN state update: K=16 bf16 MFMA (no lane masking/zero fill), 17 LDS reads in flight with counted waits
# speedup vs baseline: 1.0426x; 1.0052x over previous
.LBB0_73:
	s_mul_hi_i32 s0, s12, 0x92492493
	s_add_i32 s0, s0, s12
	s_lshr_b32 s1, s0, 31
	s_ashr_i32 s0, s0, 2
	s_add_i32 s4, s0, s1
	s_mul_i32 s0, s4, 7
	v_mov_b32_e32 v0, v176
	s_sub_i32 s3, s12, s0
	s_ashr_i32 s13, s4, 2
	s_and_b32 s14, s4, 3
	v_and_b32_e32 v3, 0x7f, v0
	s_lshl_b32 s0, s3, 8
	s_lshl_b32 s5, s13, 11
	v_ashrrev_i32_e32 v60, 7, v0
	v_lshlrev_b32_e32 v13, 2, v3
	s_add_i32 s0, s5, s0
	v_lshlrev_b32_e32 v12, 2, v60
	v_lshl_or_b32 v4, s14, 9, v13
	v_mov_b32_e32 v5, v2
	v_add_u32_e32 v1, s0, v12
	v_lshl_add_u64 v[56:57], s[82:83], 0, v[4:5]
	v_mad_i64_i32 v[4:5], s[0:1], v1, s96, v[56:57]
	v_or_b32_e32 v14, 1, v1
	v_or_b32_e32 v15, 2, v1
	v_or_b32_e32 v16, 3, v1
	v_add_u32_e32 v17, 16, v1
	v_mad_i64_i32 v[6:7], s[0:1], v14, s96, v[56:57]
	v_mad_i64_i32 v[8:9], s[0:1], v15, s96, v[56:57]
	v_mad_i64_i32 v[10:11], s[0:1], v16, s96, v[56:57]
	global_load_dword v50, v[4:5], off
	global_load_dword v51, v[6:7], off
	global_load_dword v52, v[8:9], off
	global_load_dword v53, v[10:11], off
	v_mad_i64_i32 v[4:5], s[0:1], v17, s96, v[56:57]
	v_add_u32_e32 v18, 17, v1
	v_add_u32_e32 v19, 18, v1
	v_add_u32_e32 v20, 19, v1
	v_mad_i64_i32 v[6:7], s[0:1], v18, s96, v[56:57]
	v_mad_i64_i32 v[8:9], s[0:1], v19, s96, v[56:57]
	global_load_dword v46, v[4:5], off
	global_load_dword v47, v[6:7], off
	global_load_dword v48, v[8:9], off
	v_mad_i64_i32 v[4:5], s[0:1], v20, s96, v[56:57]
	global_load_dword v49, v[4:5], off
	v_readfirstlane_b32 s0, v0
	s_ashr_i32 s2, s0, 6
	s_lshl_b32 s0, s14, 8
	s_add_u32 s0, s80, s0
	s_addc_u32 s1, s81, 0
	v_lshlrev_b32_e32 v4, 1, v3
	v_mov_b32_e32 v5, v2
	v_lshl_add_u64 v[58:59], s[0:1], 0, v[4:5]
	v_mad_i64_i32 v[10:11], s[0:1], v16, s30, v[58:59]
	v_mad_i64_i32 v[4:5], s[0:1], v1, s30, v[58:59]
	v_mad_i64_i32 v[6:7], s[0:1], v14, s30, v[58:59]
	v_mad_i64_i32 v[8:9], s[0:1], v15, s30, v[58:59]
	global_load_ushort v78, v[10:11], off
	global_load_ushort v77, v[8:9], off
	global_load_ushort v45, v[6:7], off
	global_load_ushort v44, v[4:5], off
	v_mad_i64_i32 v[10:11], s[0:1], v20, s30, v[58:59]
	v_mad_i64_i32 v[4:5], s[0:1], v17, s30, v[58:59]
	v_mad_i64_i32 v[6:7], s[0:1], v18, s30, v[58:59]
	v_mad_i64_i32 v[8:9], s[0:1], v19, s30, v[58:59]
	global_load_ushort v67, v[10:11], off
	global_load_ushort v65, v[8:9], off
	global_load_ushort v66, v[6:7], off
	global_load_ushort v64, v[4:5], off
	v_add_u32_e32 v62, 0, v13
	s_movk_i32 s0, 0x80
	v_mad_u32_u24 v70, v3, 44, v62
	v_mul_i32_i24_e32 v71, 0xffffffd4, v3
	v_cmp_gt_u32_e64 s[38:39], s0, v0
	s_mulk_i32 s4, 0x700
	v_and_b32_e32 v1, 63, v0
	v_and_b32_e32 v69, 48, v0
	v_lshl_add_u32 v63, v0, 2, 0
	v_cmp_lt_u32_e64 s[40:41], s51, v0
	v_lshl_add_u32 v61, v60, 3, v70
	v_cmp_gt_u32_e32 vcc, 32, v1
	s_mov_b32 s15, 0
	v_mov_b32_e32 v8, 0
	v_mov_b32_e32 v16, 0
	v_mov_b32_e32 v20, 0
	v_mov_b32_e32 v24, 0
	v_mov_b32_e32 v28, 0
	v_mov_b32_e32 v32, 0
	s_waitcnt vmcnt(0)
	v_sub_f32_e32 v4, 1.0, v50
	v_max_f32_e32 v83, 0xda24260, v4
	v_sub_f32_e32 v4, 1.0, v51
	v_max_f32_e32 v82, 0xda24260, v4
	v_sub_f32_e32 v5, 1.0, v52
	v_sub_f32_e32 v6, 1.0, v53
	v_max_f32_e32 v81, 0xda24260, v5
	v_max_f32_e32 v79, 0xda24260, v6
	v_sub_f32_e32 v4, 1.0, v46
	v_max_f32_e32 v76, 0xda24260, v4
	v_sub_f32_e32 v4, 1.0, v47
	v_max_f32_e32 v74, 0xda24260, v4
	v_sub_f32_e32 v4, 1.0, v48
	v_max_f32_e32 v73, 0xda24260, v4
	v_sub_f32_e32 v4, 1.0, v49
	v_max_f32_e32 v72, 0xda24260, v4
	v_and_b32_e32 v4, 15, v0
	v_lshl_or_b32 v3, s2, 4, v4
	v_mad_u64_u32 v[54:55], s[0:1], v3, 48, v[2:3]
	s_lshl_b32 s0, s12, 8
	s_add_i32 s5, s5, s0
	v_add_u32_e32 v3, s5, v12
	v_subrev_u32_e32 v75, s4, v3
	v_mov_b32_e32 v3, 0
	v_add_u32_e32 v55, 0, v69
	v_mul_u32_u24_e32 v68, 48, v4
	v_mov_b32_e32 v4, 0
	v_mov_b32_e32 v5, v3
	v_mov_b32_e32 v6, v3
	v_mov_b32_e32 v7, v3
	v_mov_b32_e32 v9, v3
	v_mov_b32_e32 v10, v3
	v_mov_b32_e32 v11, v3
	v_mov_b32_e32 v12, 0
	v_mov_b32_e32 v13, v3
	v_mov_b32_e32 v14, v3
	v_mov_b32_e32 v15, v3
	v_mov_b32_e32 v17, v3
	v_mov_b32_e32 v18, v3
	v_mov_b32_e32 v19, v3
	v_mov_b32_e32 v21, v3
	v_mov_b32_e32 v22, v3
	v_mov_b32_e32 v23, v3
	v_mov_b32_e32 v25, v3
	v_mov_b32_e32 v26, v3
	v_mov_b32_e32 v27, v3
	v_mov_b32_e32 v29, v3
	v_mov_b32_e32 v30, v3
	v_mov_b32_e32 v31, v3
	v_mov_b32_e32 v33, v3
	v_mov_b32_e32 v34, v3
	v_mov_b32_e32 v35, v3
	v_lshrrev_b32_e32 v160, 1, v69
	v_add_u32_e32 v161, v68, v160
	v_add_u32_e32 v160, v54, v160
	s_branch .LBB0_75
.LBB0_74:
	s_waitcnt vmcnt(7)
	v_sub_f32_e32 v44, 1.0, v46
	v_max_f32_e32 v76, 0xda24260, v44
	s_waitcnt vmcnt(5)
	v_sub_f32_e32 v44, 1.0, v47
	v_max_f32_e32 v74, 0xda24260, v44
	s_waitcnt vmcnt(3)
	v_sub_f32_e32 v44, 1.0, v48
	v_max_f32_e32 v73, 0xda24260, v44
	s_waitcnt vmcnt(1)
	v_sub_f32_e32 v44, 1.0, v49
	s_waitcnt lgkmcnt(0)
	v_pk_mul_f32 v[6:7], v[6:7], v[220:221]
	v_pk_mul_f32 v[4:5], v[4:5], v[218:219]
	v_max_f32_e32 v72, 0xda24260, v44
	v_sub_f32_e32 v44, 1.0, v50
	v_mfma_f32_16x16x16_bf16 v[4:7], v[236:237], v[238:239], v[4:7]
	v_max_f32_e32 v83, 0xda24260, v44
	v_and_b32_e32 v44, 0xffff, v77
	v_sub_f32_e32 v77, 1.0, v52
	s_waitcnt lgkmcnt(0)
	s_barrier
	v_and_b32_e32 v66, 0xffff, v65
	v_and_b32_e32 v65, 0xffff, v67
	s_waitcnt vmcnt(0)
	v_and_b32_e32 v67, 0xffff, v81
	v_sub_f32_e32 v45, 1.0, v51
	v_max_f32_e32 v81, 0xda24260, v77
	v_and_b32_e32 v77, 0xffff, v78
	v_sub_f32_e32 v78, 1.0, v53
	s_add_i32 s15, s15, 32
	v_and_b32_e32 v64, 0xffff, v64
	v_max_f32_e32 v82, 0xda24260, v45
	v_and_b32_e32 v45, 0xffff, v79
	v_max_f32_e32 v79, 0xda24260, v78
	v_and_b32_e32 v78, 0xffff, v80
	s_cmpk_eq_i32 s15, 0xe0
	s_cbranch_scc1 .LBB0_135

.LBB0_85:
	s_or_b64 exec, exec, s[0:1]
	v_add_u32_e32 v81, s15, v75
	v_add_u32_e32 v38, 32, v81
	v_mad_i64_i32 v[36:37], s[0:1], v38, s96, v[56:57]
	global_load_dword v50, v[36:37], off
	v_mad_i64_i32 v[36:37], s[0:1], v38, s30, v[58:59]
	v_add_u32_e32 v38, 33, v81
	global_load_ushort v77, v[36:37], off
	v_mad_i64_i32 v[36:37], s[0:1], v38, s96, v[56:57]
	global_load_dword v51, v[36:37], off
	v_mad_i64_i32 v[36:37], s[0:1], v38, s30, v[58:59]
	v_add_u32_e32 v38, 34, v81
	global_load_ushort v79, v[36:37], off
	v_mad_i64_i32 v[36:37], s[0:1], v38, s96, v[56:57]
	global_load_dword v52, v[36:37], off
	v_mad_i64_i32 v[36:37], s[0:1], v38, s30, v[58:59]
	v_add_u32_e32 v38, 35, v81
	global_load_ushort v78, v[36:37], off
	v_mad_i64_i32 v[36:37], s[0:1], v38, s96, v[56:57]
	global_load_dword v53, v[36:37], off
	v_mad_i64_i32 v[36:37], s[0:1], v38, s30, v[58:59]
	global_load_ushort v80, v[36:37], off
	s_waitcnt lgkmcnt(0)
	s_barrier
	ds_read_b64 v[238:239], v160 offset:14848
	ds_read_b64 v[222:223], v161 offset:8704
	ds_read_b128 v[190:193], v55 offset:20992
	ds_read_b64 v[224:225], v161 offset:9472
	ds_read_b128 v[194:197], v55 offset:21056
	ds_read_b64 v[226:227], v161 offset:10240
	ds_read_b128 v[198:201], v55 offset:21120
	ds_read_b64 v[228:229], v161 offset:11008
	ds_read_b128 v[202:205], v55 offset:21184
	ds_read_b64 v[230:231], v161 offset:11776
	ds_read_b128 v[206:209], v55 offset:21248
	ds_read_b64 v[232:233], v161 offset:12544
	ds_read_b128 v[210:213], v55 offset:21312
	s_waitcnt lgkmcnt(10)
	v_pk_mul_f32 v[34:35], v[34:35], v[192:193]
	v_pk_mul_f32 v[32:33], v[32:33], v[190:191]
	s_nop 1
	v_mfma_f32_16x16x16_bf16 v[32:35], v[222:223], v[238:239], v[32:35]
	ds_read_b64 v[234:235], v161 offset:13312
	ds_read_b128 v[214:217], v55 offset:21376
	s_waitcnt lgkmcnt(10)
	v_pk_mul_f32 v[30:31], v[30:31], v[196:197]
	v_pk_mul_f32 v[28:29], v[28:29], v[194:195]
	s_nop 1
	v_mfma_f32_16x16x16_bf16 v[28:31], v[224:225], v[238:239], v[28:31]
	ds_read_b64 v[236:237], v161 offset:14080
	ds_read_b128 v[218:221], v55 offset:21440
	s_waitcnt lgkmcnt(10)
	v_pk_mul_f32 v[26:27], v[26:27], v[200:201]
	v_pk_mul_f32 v[24:25], v[24:25], v[198:199]
	s_nop 1
	v_mfma_f32_16x16x16_bf16 v[24:27], v[226:227], v[238:239], v[24:27]
	s_waitcnt lgkmcnt(8)
	v_pk_mul_f32 v[22:23], v[22:23], v[204:205]
	v_pk_mul_f32 v[20:21], v[20:21], v[202:203]
	s_nop 1
	v_mfma_f32_16x16x16_bf16 v[20:23], v[228:229], v[238:239], v[20:23]
	s_waitcnt lgkmcnt(6)
	v_pk_mul_f32 v[18:19], v[18:19], v[208:209]
	v_pk_mul_f32 v[16:17], v[16:17], v[206:207]
	s_nop 1
	v_mfma_f32_16x16x16_bf16 v[16:19], v[230:231], v[238:239], v[16:19]
	s_waitcnt lgkmcnt(4)
	v_pk_mul_f32 v[14:15], v[14:15], v[212:213]
	v_pk_mul_f32 v[12:13], v[12:13], v[210:211]
	s_nop 1
	v_mfma_f32_16x16x16_bf16 v[12:15], v[232:233], v[238:239], v[12:15]
	s_waitcnt lgkmcnt(2)
	v_pk_mul_f32 v[10:11], v[10:11], v[216:217]
	v_pk_mul_f32 v[8:9], v[8:9], v[214:215]
	s_nop 1
	v_mfma_f32_16x16x16_bf16 v[8:11], v[234:235], v[238:239], v[8:11]
	v_cmp_gt_f32_e64 s[0:1], s34, v76
	s_waitcnt lgkmcnt(0)
	s_barrier
	v_pk_mul_f32 v[6:7], v[6:7], v[220:221]
	v_pk_mul_f32 v[4:5], v[4:5], v[218:219]
	s_nop 1
	v_mfma_f32_16x16x16_bf16 v[4:7], v[236:237], v[238:239], v[4:7]
	v_cndmask_b32_e64 v36, 0, 32, s[0:1]
	v_ldexp_f32 v36, v76, v36
	v_log_f32_e32 v36, v36
	s_nop 0
	v_mul_f32_e32 v37, 0x3f317217, v36
	v_fma_f32 v37, v36, s97, -v37
	v_fmac_f32_e32 v37, 0x3377d1cf, v36
	v_fmac_f32_e32 v37, 0x3f317217, v36
	v_cmp_lt_f32_e64 s[42:43], |v36|, s35
	s_nop 1
	v_cndmask_b32_e64 v36, v36, v37, s[42:43]
	v_cndmask_b32_e64 v37, 0, v188, s[0:1]
	v_sub_f32_e32 v36, v36, v37
	v_cmp_gt_f32_e64 s[0:1], s34, v74
	v_add_f32_e32 v42, 0, v36
	s_nop 0
	v_cndmask_b32_e64 v36, 0, 32, s[0:1]
	v_ldexp_f32 v36, v74, v36
	v_log_f32_e32 v36, v36
	s_nop 0
	v_mul_f32_e32 v37, 0x3f317217, v36
	v_fma_f32 v37, v36, s97, -v37
	v_fmac_f32_e32 v37, 0x3377d1cf, v36
	v_fmac_f32_e32 v37, 0x3f317217, v36
	v_cmp_lt_f32_e64 s[42:43], |v36|, s35
	s_nop 1
	v_cndmask_b32_e64 v36, v36, v37, s[42:43]
	v_cndmask_b32_e64 v37, 0, v188, s[0:1]
	v_sub_f32_e32 v36, v36, v37
	v_cmp_gt_f32_e64 s[0:1], s34, v73
	v_add_f32_e32 v43, v36, v42
	s_nop 0
	v_cndmask_b32_e64 v36, 0, 32, s[0:1]
	v_ldexp_f32 v36, v73, v36
	v_log_f32_e32 v36, v36
	s_nop 0
	v_mul_f32_e32 v37, 0x3f317217, v36
	v_fma_f32 v37, v36, s97, -v37
	v_fmac_f32_e32 v37, 0x3377d1cf, v36
	v_fmac_f32_e32 v37, 0x3f317217, v36
	v_cmp_lt_f32_e64 s[42:43], |v36|, s35
	s_nop 1
	v_cndmask_b32_e64 v36, v36, v37, s[42:43]
	v_cndmask_b32_e64 v37, 0, v188, s[0:1]
	v_sub_f32_e32 v36, v36, v37
	v_cmp_gt_f32_e64 s[0:1], s34, v72
	v_add_f32_e32 v73, v36, v43
	s_nop 0
	v_cndmask_b32_e64 v36, 0, 32, s[0:1]
	v_ldexp_f32 v36, v72, v36
	v_log_f32_e32 v36, v36
	s_nop 0
	v_mul_f32_e32 v37, 0x3f317217, v36
	v_fma_f32 v37, v36, s97, -v37
	v_fmac_f32_e32 v37, 0x3377d1cf, v36
	v_fmac_f32_e32 v37, 0x3f317217, v36
	v_cmp_lt_f32_e64 s[42:43], |v36|, s35
	s_nop 1
	v_cndmask_b32_e64 v36, v36, v37, s[42:43]
	v_cndmask_b32_e64 v37, 0, v188, s[0:1]
	v_sub_f32_e32 v36, v36, v37
	v_add_f32_e32 v37, v36, v73
	ds_write_b32 v63, v37 offset:21504
	s_waitcnt lgkmcnt(0)
	s_barrier
	ds_read2st64_b32 v[38:39], v62 offset0:84 offset1:86
	ds_read2st64_b32 v[40:41], v62 offset0:88 offset1:90
	s_and_saveexec_b64 s[4:5], s[40:41]
	s_cbranch_execz .LBB0_111
	v_cmp_lt_i32_e64 s[0:1], 1, v60
	s_mov_b64 s[6:7], 0
	s_and_saveexec_b64 s[8:9], s[0:1]
	s_xor_b64 s[8:9], exec, s[8:9]
	s_cbranch_execz .LBB0_133
	v_cmp_eq_u32_e64 s[0:1], 2, v60
	s_mov_b64 s[6:7], -1
	s_and_saveexec_b64 s[10:11], s[0:1]
	s_cbranch_execz .LBB0_107
	s_waitcnt lgkmcnt(1)
	v_add_f32_e32 v45, v38, v39
	s_xor_b64 s[6:7], exec, -1

.LBB0_113:
	s_or_b64 exec, exec, s[0:1]
	v_add_u32_e32 v38, 48, v81
	v_mad_i64_i32 v[36:37], s[0:1], v38, s96, v[56:57]
	global_load_dword v46, v[36:37], off
	v_mad_i64_i32 v[36:37], s[0:1], v38, s30, v[58:59]
	v_add_u32_e32 v38, 49, v81
	global_load_ushort v64, v[36:37], off
	v_mad_i64_i32 v[36:37], s[0:1], v38, s96, v[56:57]
	global_load_dword v47, v[36:37], off
	v_mad_i64_i32 v[36:37], s[0:1], v38, s30, v[58:59]
	v_add_u32_e32 v38, 50, v81
	global_load_ushort v65, v[36:37], off
	v_mad_i64_i32 v[36:37], s[0:1], v38, s96, v[56:57]
	global_load_dword v48, v[36:37], off
	v_mad_i64_i32 v[36:37], s[0:1], v38, s30, v[58:59]
	v_add_u32_e32 v38, 51, v81
	global_load_ushort v67, v[36:37], off
	v_mad_i64_i32 v[36:37], s[0:1], v38, s96, v[56:57]
	global_load_dword v49, v[36:37], off
	v_mad_i64_i32 v[36:37], s[0:1], v38, s30, v[58:59]
	global_load_ushort v81, v[36:37], off
	s_waitcnt lgkmcnt(0)
	s_barrier
	ds_read_b64 v[238:239], v160 offset:14848
	ds_read_b64 v[222:223], v161 offset:8704
	ds_read_b128 v[190:193], v55 offset:20992
	ds_read_b64 v[224:225], v161 offset:9472
	ds_read_b128 v[194:197], v55 offset:21056
	ds_read_b64 v[226:227], v161 offset:10240
	ds_read_b128 v[198:201], v55 offset:21120
	ds_read_b64 v[228:229], v161 offset:11008
	ds_read_b128 v[202:205], v55 offset:21184
	ds_read_b64 v[230:231], v161 offset:11776
	ds_read_b128 v[206:209], v55 offset:21248
	ds_read_b64 v[232:233], v161 offset:12544
	ds_read_b128 v[210:213], v55 offset:21312
	s_waitcnt lgkmcnt(10)
	v_pk_mul_f32 v[34:35], v[34:35], v[192:193]
	v_pk_mul_f32 v[32:33], v[32:33], v[190:191]
	s_nop 1
	v_mfma_f32_16x16x16_bf16 v[32:35], v[222:223], v[238:239], v[32:35]
	ds_read_b64 v[234:235], v161 offset:13312
	ds_read_b128 v[214:217], v55 offset:21376
	s_waitcnt lgkmcnt(10)
	v_pk_mul_f32 v[30:31], v[30:31], v[196:197]
	v_pk_mul_f32 v[28:29], v[28:29], v[194:195]
	s_nop 1
	v_mfma_f32_16x16x16_bf16 v[28:31], v[224:225], v[238:239], v[28:31]
	ds_read_b64 v[236:237], v161 offset:14080
	ds_read_b128 v[218:221], v55 offset:21440
	s_waitcnt lgkmcnt(10)
	v_pk_mul_f32 v[26:27], v[26:27], v[200:201]
	v_pk_mul_f32 v[24:25], v[24:25], v[198:199]
	s_nop 1
	v_mfma_f32_16x16x16_bf16 v[24:27], v[226:227], v[238:239], v[24:27]
	s_waitcnt lgkmcnt(8)
	v_pk_mul_f32 v[22:23], v[22:23], v[204:205]
	v_pk_mul_f32 v[20:21], v[20:21], v[202:203]
	s_nop 1
	v_mfma_f32_16x16x16_bf16 v[20:23], v[228:229], v[238:239], v[20:23]
	s_waitcnt lgkmcnt(6)
	v_pk_mul_f32 v[18:19], v[18:19], v[208:209]
	v_pk_mul_f32 v[16:17], v[16:17], v[206:207]
	s_nop 1
	v_mfma_f32_16x16x16_bf16 v[16:19], v[230:231], v[238:239], v[16:19]
	s_waitcnt lgkmcnt(4)
	v_pk_mul_f32 v[14:15], v[14:15], v[212:213]
	v_pk_mul_f32 v[12:13], v[12:13], v[210:211]
	s_nop 1
	v_mfma_f32_16x16x16_bf16 v[12:15], v[232:233], v[238:239], v[12:15]
	s_waitcnt lgkmcnt(2)
	v_pk_mul_f32 v[10:11], v[10:11], v[216:217]
	v_pk_mul_f32 v[8:9], v[8:9], v[214:215]
	s_nop 1
	v_mfma_f32_16x16x16_bf16 v[8:11], v[234:235], v[238:239], v[8:11]
	s_branch .LBB0_74

.LBB0_145:
	s_or_b64 exec, exec, s[0:1]
	s_waitcnt lgkmcnt(0)
	s_barrier
	ds_read_b64 v[238:239], v160 offset:14848
	ds_read_b64 v[222:223], v161 offset:8704
	ds_read_b128 v[190:193], v55 offset:20992
	ds_read_b64 v[224:225], v161 offset:9472
	ds_read_b128 v[194:197], v55 offset:21056
	ds_read_b64 v[226:227], v161 offset:10240
	ds_read_b128 v[198:201], v55 offset:21120
	ds_read_b64 v[228:229], v161 offset:11008
	ds_read_b128 v[202:205], v55 offset:21184
	ds_read_b64 v[230:231], v161 offset:11776
	ds_read_b128 v[206:209], v55 offset:21248
	ds_read_b64 v[232:233], v161 offset:12544
	ds_read_b128 v[210:213], v55 offset:21312
	s_waitcnt lgkmcnt(10)
	v_pk_mul_f32 v[34:35], v[34:35], v[192:193]
	v_pk_mul_f32 v[32:33], v[32:33], v[190:191]
	s_nop 1
	v_mfma_f32_16x16x16_bf16 v[32:35], v[222:223], v[238:239], v[32:35]
	ds_read_b64 v[234:235], v161 offset:13312
	ds_read_b128 v[214:217], v55 offset:21376
	s_waitcnt lgkmcnt(10)
	v_pk_mul_f32 v[30:31], v[30:31], v[196:197]
	v_pk_mul_f32 v[28:29], v[28:29], v[194:195]
	s_nop 1
	v_mfma_f32_16x16x16_bf16 v[28:31], v[224:225], v[238:239], v[28:31]
	ds_read_b64 v[236:237], v161 offset:14080
	ds_read_b128 v[218:221], v55 offset:21440
	s_waitcnt lgkmcnt(10)
	v_pk_mul_f32 v[26:27], v[26:27], v[200:201]
	v_pk_mul_f32 v[24:25], v[24:25], v[198:199]
	s_nop 1
	v_mfma_f32_16x16x16_bf16 v[24:27], v[226:227], v[238:239], v[24:27]
	s_waitcnt lgkmcnt(8)
	v_pk_mul_f32 v[22:23], v[22:23], v[204:205]
	v_pk_mul_f32 v[20:21], v[20:21], v[202:203]
	s_nop 1
	v_mfma_f32_16x16x16_bf16 v[20:23], v[228:229], v[238:239], v[20:23]
	s_waitcnt lgkmcnt(6)
	v_pk_mul_f32 v[18:19], v[18:19], v[208:209]
	v_pk_mul_f32 v[16:17], v[16:17], v[206:207]
	s_nop 1
	v_mfma_f32_16x16x16_bf16 v[16:19], v[230:231], v[238:239], v[16:19]
	s_waitcnt lgkmcnt(4)
	v_pk_mul_f32 v[14:15], v[14:15], v[212:213]
	v_pk_mul_f32 v[12:13], v[12:13], v[210:211]
	s_nop 1
	v_mfma_f32_16x16x16_bf16 v[12:15], v[232:233], v[238:239], v[12:15]
	s_waitcnt lgkmcnt(2)
	v_pk_mul_f32 v[10:11], v[10:11], v[216:217]
	v_pk_mul_f32 v[8:9], v[8:9], v[214:215]
	s_nop 1
	v_mfma_f32_16x16x16_bf16 v[8:11], v[234:235], v[238:239], v[8:11]
	v_cmp_gt_f32_e64 s[0:1], s34, v76
	s_waitcnt lgkmcnt(0)
	s_barrier
	v_pk_mul_f32 v[6:7], v[6:7], v[220:221]
	v_pk_mul_f32 v[4:5], v[4:5], v[218:219]
	s_nop 1
	v_mfma_f32_16x16x16_bf16 v[4:7], v[236:237], v[238:239], v[4:7]
	v_cndmask_b32_e64 v36, 0, 32, s[0:1]
	v_ldexp_f32 v36, v76, v36
	v_log_f32_e32 v36, v36
	s_nop 0
	v_mul_f32_e32 v37, 0x3f317217, v36
	v_fma_f32 v37, v36, s97, -v37
	v_fmac_f32_e32 v37, 0x3377d1cf, v36
	v_fmac_f32_e32 v37, 0x3f317217, v36
	v_cmp_lt_f32_e64 s[42:43], |v36|, s35
	s_nop 1
	v_cndmask_b32_e64 v36, v36, v37, s[42:43]
	v_cndmask_b32_e64 v37, 0, v188, s[0:1]
	v_sub_f32_e32 v36, v36, v37
	v_cmp_gt_f32_e64 s[0:1], s34, v74
	v_add_f32_e32 v42, 0, v36
	s_nop 0
	v_cndmask_b32_e64 v36, 0, 32, s[0:1]
	v_ldexp_f32 v36, v74, v36
	v_log_f32_e32 v36, v36
	s_nop 0
	v_mul_f32_e32 v37, 0x3f317217, v36
	v_fma_f32 v37, v36, s97, -v37
	v_fmac_f32_e32 v37, 0x3377d1cf, v36
	v_fmac_f32_e32 v37, 0x3f317217, v36
	v_cmp_lt_f32_e64 s[42:43], |v36|, s35
	s_nop 1
	v_cndmask_b32_e64 v36, v36, v37, s[42:43]
	v_cndmask_b32_e64 v37, 0, v188, s[0:1]
	v_sub_f32_e32 v36, v36, v37
	v_cmp_gt_f32_e64 s[0:1], s34, v73
	v_add_f32_e32 v43, v42, v36
	s_nop 0
	v_cndmask_b32_e64 v36, 0, 32, s[0:1]
	v_ldexp_f32 v36, v73, v36
	v_log_f32_e32 v36, v36
	s_nop 0
	v_mul_f32_e32 v37, 0x3f317217, v36
	v_fma_f32 v37, v36, s97, -v37
	v_fmac_f32_e32 v37, 0x3377d1cf, v36
	v_fmac_f32_e32 v37, 0x3f317217, v36
	v_cmp_lt_f32_e64 s[42:43], |v36|, s35
	s_nop 1
	v_cndmask_b32_e64 v36, v36, v37, s[42:43]
	v_cndmask_b32_e64 v37, 0, v188, s[0:1]
	v_sub_f32_e32 v36, v36, v37
	v_cmp_gt_f32_e64 s[0:1], s34, v72
	v_add_f32_e32 v53, v43, v36
	s_nop 0
	v_cndmask_b32_e64 v36, 0, 32, s[0:1]
	v_ldexp_f32 v36, v72, v36
	v_log_f32_e32 v36, v36
	s_nop 0
	v_mul_f32_e32 v37, 0x3f317217, v36
	v_fma_f32 v37, v36, s97, -v37
	v_fmac_f32_e32 v37, 0x3377d1cf, v36
	v_fmac_f32_e32 v37, 0x3f317217, v36
	v_cmp_lt_f32_e64 s[42:43], |v36|, s35
	s_nop 1
	v_cndmask_b32_e64 v36, v36, v37, s[42:43]
	v_cndmask_b32_e64 v37, 0, v188, s[0:1]
	v_sub_f32_e32 v36, v36, v37
	v_add_f32_e32 v37, v53, v36
	ds_write_b32 v63, v37 offset:21504
	s_waitcnt lgkmcnt(0)
	s_barrier
	ds_read2st64_b32 v[38:39], v62 offset0:84 offset1:86
	ds_read2st64_b32 v[40:41], v62 offset0:88 offset1:90
	s_and_saveexec_b64 s[4:5], s[40:41]
	s_cbranch_execz .LBB0_171
	v_cmp_lt_i32_e64 s[0:1], 1, v60
	s_mov_b64 s[6:7], 0
	s_and_saveexec_b64 s[8:9], s[0:1]
	s_xor_b64 s[8:9], exec, s[8:9]
	s_cbranch_execz .LBB0_195
	v_cmp_eq_u32_e64 s[0:1], 2, v60
	s_mov_b64 s[6:7], -1
	s_and_saveexec_b64 s[10:11], s[0:1]
	s_cbranch_execz .LBB0_167
	s_waitcnt lgkmcnt(1)
	v_add_f32_e32 v45, v38, v39
	s_xor_b64 s[6:7], exec, -1

.LBB0_173:
	s_or_b64 exec, exec, s[0:1]
	s_waitcnt lgkmcnt(0)
	s_barrier
	ds_read_b64 v[238:239], v160 offset:14848
	ds_read_b64 v[222:223], v161 offset:8704
	ds_read_b128 v[190:193], v55 offset:20992
	ds_read_b64 v[224:225], v161 offset:9472
	ds_read_b128 v[194:197], v55 offset:21056
	ds_read_b64 v[226:227], v161 offset:10240
	ds_read_b128 v[198:201], v55 offset:21120
	ds_read_b64 v[228:229], v161 offset:11008
	ds_read_b128 v[202:205], v55 offset:21184
	ds_read_b64 v[230:231], v161 offset:11776
	ds_read_b128 v[206:209], v55 offset:21248
	ds_read_b64 v[232:233], v161 offset:12544
	ds_read_b128 v[210:213], v55 offset:21312
	s_waitcnt lgkmcnt(10)
	v_pk_mul_f32 v[34:35], v[34:35], v[192:193]
	v_pk_mul_f32 v[32:33], v[32:33], v[190:191]
	s_nop 1
	v_mfma_f32_16x16x16_bf16 v[32:35], v[222:223], v[238:239], v[32:35]
	ds_read_b64 v[234:235], v161 offset:13312
	ds_read_b128 v[214:217], v55 offset:21376
	s_waitcnt lgkmcnt(10)
	v_pk_mul_f32 v[30:31], v[30:31], v[196:197]
	v_pk_mul_f32 v[28:29], v[28:29], v[194:195]
	s_nop 1
	v_mfma_f32_16x16x16_bf16 v[28:31], v[224:225], v[238:239], v[28:31]
	ds_read_b64 v[236:237], v161 offset:14080
	ds_read_b128 v[218:221], v55 offset:21440
	s_waitcnt lgkmcnt(10)
	v_pk_mul_f32 v[26:27], v[26:27], v[200:201]
	v_pk_mul_f32 v[24:25], v[24:25], v[198:199]
	s_nop 1
	v_mfma_f32_16x16x16_bf16 v[24:27], v[226:227], v[238:239], v[24:27]
	s_waitcnt lgkmcnt(8)
	v_pk_mul_f32 v[22:23], v[22:23], v[204:205]
	v_pk_mul_f32 v[20:21], v[20:21], v[202:203]
	s_nop 1
	v_mfma_f32_16x16x16_bf16 v[20:23], v[228:229], v[238:239], v[20:23]
	s_waitcnt lgkmcnt(6)
	v_pk_mul_f32 v[18:19], v[18:19], v[208:209]
	v_pk_mul_f32 v[16:17], v[16:17], v[206:207]
	s_nop 1
	v_mfma_f32_16x16x16_bf16 v[16:19], v[230:231], v[238:239], v[16:19]
	s_waitcnt lgkmcnt(4)
	v_pk_mul_f32 v[14:15], v[14:15], v[212:213]
	v_pk_mul_f32 v[12:13], v[12:13], v[210:211]
	s_nop 1
	v_mfma_f32_16x16x16_bf16 v[12:15], v[232:233], v[238:239], v[12:15]
	s_waitcnt lgkmcnt(2)
	v_pk_mul_f32 v[10:11], v[10:11], v[216:217]
	v_pk_mul_f32 v[8:9], v[8:9], v[214:215]
	s_nop 1
	v_mfma_f32_16x16x16_bf16 v[8:11], v[234:235], v[238:239], v[8:11]
	s_lshl_b32 s0, s13, 5
	s_lshl_b32 s1, s14, 3
	s_add_i32 s0, s0, s3
	s_add_i32 s0, s0, s1
	s_ashr_i32 s1, s0, 31
	s_lshl_b64 s[4:5], s[0:1], 16
	v_readlane_b32 s3, v253, 8
	s_add_u32 s4, s3, s4
	v_readlane_b32 s3, v253, 9
	s_addc_u32 s5, s3, s5
	s_ashr_i32 s3, s2, 31
	s_lshl_b64 s[2:3], s[2:3], 13
	s_waitcnt lgkmcnt(0)
	v_pk_mul_f32 v[6:7], v[6:7], v[220:221]
	v_pk_mul_f32 v[4:5], v[4:5], v[218:219]
	s_add_u32 s2, s4, s2
	s_addc_u32 s3, s5, s3
	v_mfma_f32_16x16x16_bf16 v[4:7], v[236:237], v[238:239], v[4:7]
	v_lshlrev_b32_e32 v36, 4, v1
	v_mov_b32_e32 v37, v2
	s_waitcnt lgkmcnt(0)
	s_barrier
	v_lshl_add_u64 v[38:39], s[2:3], 0, v[36:37]
	global_store_dwordx4 v36, v[32:35], s[2:3]
	global_store_dwordx4 v36, v[28:31], s[2:3] offset:1024
	global_store_dwordx4 v36, v[24:27], s[2:3] offset:2048
	global_store_dwordx4 v36, v[20:23], s[2:3] offset:3072
	s_nop 1
	v_add_co_u32_e32 v20, vcc, 0x1000, v38
	s_nop 1
	v_addc_co_u32_e32 v21, vcc, 0, v39, vcc
	global_store_dwordx4 v[20:21], v[16:19], off
	global_store_dwordx4 v[20:21], v[12:15], off offset:1024
	global_store_dwordx4 v[20:21], v[8:11], off offset:2048
	global_store_dwordx4 v[20:21], v[4:7], off offset:3072
	s_and_saveexec_b64 s[2:3], s[38:39]
	s_cbranch_execz .LBB0_72
	v_mul_f32_e32 v1, 0x3fb8aa3b, v3
	v_exp_f32_e32 v3, v1
	s_lshl_b64 s[0:1], s[0:1], 9
	v_readlane_b32 s4, v253, 10
	s_add_u32 s0, s4, s0
	v_readlane_b32 s4, v253, 11
	s_addc_u32 s1, s4, s1
	v_mov_b32_e32 v1, v2
	v_lshl_add_u64 v[0:1], v[0:1], 2, s[0:1]
	global_store_dword v[0:1], v3, off
	s_branch .LBB0_72

.LBB0_349:
	s_ashr_i32 s52, s18, 5
	s_lshl_b32 s6, s19, 8
	s_lshl_b32 s10, s52, 11
	v_ashrrev_i32_e32 v83, 7, v3
	s_and_b32 s7, s8, 3
	s_or_b32 s6, s6, s10
	v_lshlrev_b32_e32 v78, 2, v83
	s_lshl_b32 s1, s9, 8
	v_and_b32_e32 v0, 0x7f, v3
	v_add_u32_e32 v1, s6, v78
	s_lshl_b32 s6, s7, 8
	v_lshl_or_b32 v4, s7, 7, v0
	s_add_u32 s8, s80, s6
	v_lshlrev_b32_e32 v50, 1, v4
	v_lshlrev_b32_e32 v52, 2, v4
	s_addc_u32 s9, s81, 0
	v_lshlrev_b32_e32 v4, 1, v0
	v_mov_b32_e32 v5, v2
	v_lshl_add_u64 v[54:55], s[8:9], 0, v[4:5]
	v_mov_b64_e32 v[4:5], s[82:83]
	v_or_b32_e32 v56, 1, v1
	v_or_b32_e32 v66, 2, v1
	v_mov_b32_e32 v51, v2
	v_mov_b32_e32 v53, v2
	v_mad_i64_i32 v[6:7], s[12:13], v1, s96, v[4:5]
	v_mad_i64_i32 v[46:47], s[12:13], v56, s96, v[4:5]
	v_mad_i64_i32 v[58:59], s[12:13], v56, s30, v[54:55]
	v_mad_i64_i32 v[56:57], s[12:13], v66, s96, v[4:5]
	v_lshl_add_u64 v[42:43], v[6:7], 0, v[50:51]
	v_lshl_add_u64 v[6:7], v[6:7], 0, v[52:53]
	v_lshl_add_u64 v[48:49], v[46:47], 0, v[50:51]
	v_lshl_add_u64 v[60:61], v[56:57], 0, v[52:53]
	v_mad_i64_i32 v[44:45], s[12:13], v1, s30, v[54:55]
	v_lshl_add_u64 v[46:47], v[46:47], 0, v[52:53]
	v_lshl_add_u64 v[62:63], v[56:57], 0, v[50:51]
	global_load_dword v56, v[6:7], off
	global_load_ushort v84, v[44:45], off
	global_load_ushort v67, v[48:49], off offset:2048
	global_load_dword v57, v[46:47], off
	s_waitcnt lgkmcnt(0)
	global_load_ushort v85, v[58:59], off
	s_nop 0
	global_load_dword v60, v[60:61], off
	s_nop 0
	global_load_ushort v68, v[62:63], off offset:2048
	global_load_ushort v69, v[42:43], off offset:2048
	v_or_b32_e32 v70, 3, v1
	v_add_u32_e32 v48, 16, v1
	v_mad_i64_i32 v[6:7], s[12:13], v70, s96, v[4:5]
	v_mad_i64_i32 v[44:45], s[12:13], v48, s96, v[4:5]
	v_add_u32_e32 v71, 17, v1
	v_lshl_add_u64 v[42:43], v[6:7], 0, v[50:51]
	v_lshl_add_u64 v[46:47], v[44:45], 0, v[50:51]
	v_mad_i64_i32 v[62:63], s[12:13], v71, s96, v[4:5]
	v_lshl_add_u64 v[6:7], v[6:7], 0, v[52:53]
	v_lshl_add_u64 v[44:45], v[44:45], 0, v[52:53]
	v_mad_i64_i32 v[48:49], s[12:13], v48, s30, v[54:55]
	v_lshl_add_u64 v[64:65], v[62:63], 0, v[50:51]
	global_load_ushort v72, v[42:43], off offset:2048
	global_load_dword v61, v[6:7], off
	global_load_dword v58, v[44:45], off
	global_load_ushort v86, v[48:49], off
	global_load_ushort v74, v[64:65], off offset:2048
	global_load_ushort v75, v[46:47], off offset:2048
	v_add_u32_e32 v46, 18, v1
	v_add_u32_e32 v1, 19, v1
	v_mad_i64_i32 v[42:43], s[12:13], v46, s96, v[4:5]
	v_mad_i64_i32 v[4:5], s[12:13], v1, s96, v[4:5]
	v_lshl_add_u64 v[6:7], v[62:63], 0, v[52:53]
	v_lshl_add_u64 v[44:45], v[42:43], 0, v[50:51]
	v_lshl_add_u64 v[48:49], v[4:5], 0, v[50:51]
	v_lshl_add_u64 v[4:5], v[4:5], 0, v[52:53]
	v_lshl_add_u64 v[42:43], v[42:43], 0, v[52:53]
	v_mad_i64_i32 v[46:47], s[12:13], v46, s30, v[54:55]
	v_mad_i64_i32 v[64:65], s[12:13], v1, s30, v[54:55]
	global_load_dword v59, v[6:7], off
	global_load_dword v62, v[42:43], off
	global_load_ushort v98, v[46:47], off
	global_load_ushort v1, v[48:49], off offset:2048
	global_load_dword v63, v[4:5], off
	s_waitcnt lgkmcnt(0)
	global_load_ushort v101, v[64:65], off
	s_nop 0
	global_load_ushort v44, v[44:45], off offset:2048
	v_mad_i64_i32 v[4:5], s[12:13], v66, s30, v[54:55]
	v_mad_i64_i32 v[6:7], s[12:13], v70, s30, v[54:55]
	v_readlane_b32 s11, v254, 59
	global_load_ushort v108, v[6:7], off
	global_load_ushort v107, v[4:5], off
	v_mov_b32_e32 v4, s11
	ds_read_b64 v[4:5], v4
	v_mad_i64_i32 v[6:7], s[12:13], v71, s30, v[54:55]
	v_lshlrev_b32_e32 v45, 2, v3
	v_and_b32_e32 v46, 0x7c, v45
	s_waitcnt lgkmcnt(0)
	v_readfirstlane_b32 s11, v4
	v_readfirstlane_b32 s12, v5
	s_add_u32 s11, s11, s4
	s_addc_u32 s13, s12, s5
	s_lshl_b32 s12, s7, 9
	s_add_u32 s12, s11, s12
	s_addc_u32 s13, s13, 0
	v_lshlrev_b32_e32 v42, 2, v46
	v_mov_b32_e32 v43, v2
	v_lshl_add_u64 v[4:5], s[12:13], 0, v[42:43]
	global_load_ushort v89, v[6:7], off
	v_and_b32_e32 v87, 15, v3
	flat_load_dwordx4 v[4:7], v[4:5]
	s_add_u32 s12, s62, s6
	s_movk_i32 s6, 0x80
	s_addc_u32 s13, s63, 0
	v_cmp_gt_u32_e64 s[38:39], s6, v3
	s_lshl_b32 s6, s0, 4
	v_add_u32_e32 v88, 0, v45
	v_add_u32_e32 v45, 0, v42
	v_lshlrev_b32_e32 v42, 1, v46
	s_lshl_b32 s0, s0, 6
	v_lshlrev_b32_e32 v49, 2, v82
	v_lshl_add_u32 v91, v0, 2, 0
	v_cmp_gt_u32_e64 s[42:43], 32, v40
	v_mad_u32_u24 v46, v0, 44, v91
	v_mul_i32_i24_e32 v47, 0xffffffd4, v0
	s_waitcnt vmcnt(0)
	v_sub_f32_e32 v43, 1.0, v56
	v_max_f32_e32 v109, 0xda24260, v43
	v_mov_b32_e32 v166, v67
	v_sub_f32_e32 v43, 1.0, v57
	v_max_f32_e32 v110, 0xda24260, v43
	v_sub_f32_e32 v43, 1.0, v60
	v_max_f32_e32 v111, 0xda24260, v43
	v_and_b32_e32 v96, 48, v3
	v_cmp_lt_u32_e64 s[40:41], s51, v3
	v_or_b32_e32 v90, 2, v82
	v_mov_b32_e32 v167, v69
	v_mov_b32_e32 v169, v68
	v_lshl_add_u32 v92, v83, 3, v46
	v_add_u32_e32 v97, 0, v49
	v_cmp_gt_u32_e64 s[44:45], v82, v87
	v_cmp_lt_u32_e64 s[46:47], v82, v87
	v_cmp_gt_u32_e64 s[48:49], v90, v87
	s_mov_b32 s53, 0
	v_add_u32_e32 v104, v46, v47
	v_mov_b32_e32 v168, v72
	v_sub_f32_e32 v43, 1.0, v61
	v_max_f32_e32 v113, 0xda24260, v43
	v_sub_f32_e32 v43, 1.0, v58
	v_max_f32_e32 v112, 0xda24260, v43
	v_mov_b32_e32 v171, v75
	v_mov_b32_e32 v170, v74
	s_mov_b32 s54, 0
	v_sub_f32_e32 v43, 1.0, v59
	v_max_f32_e32 v114, 0xda24260, v43
	v_sub_f32_e32 v43, 1.0, v62
	v_mov_b32_e32 v172, v1
	v_sub_f32_e32 v1, 1.0, v63
	v_max_f32_e32 v116, 0xda24260, v1
	v_mul_u32_u24_e32 v1, 0x88, v87
	v_max_f32_e32 v115, 0xda24260, v43
	v_mov_b32_e32 v43, v2
	v_lshl_add_u32 v48, v1, 1, 0
	v_or_b32_e32 v1, s6, v87
	v_lshl_add_u64 v[64:65], s[12:13], 0, v[42:43]
	v_mad_u64_u32 v[66:67], s[12:13], v1, 48, v[2:3]
	v_lshl_add_u32 v1, v87, 8, v48
	v_mov_b32_e32 v173, v44
	v_ashrrev_i32_e32 v44, 5, v3
	v_add3_u32 v95, v1, s0, v49
	s_movk_i32 s0, 0x210
	v_mul_lo_u32 v40, v44, s0
	s_movk_i32 s0, 0x220
	v_mad_u64_u32 v[0:1], s[12:13], v83, s0, v[0:1]
	v_lshl_add_u32 v93, v41, 4, v48
	v_lshlrev_b32_e32 v41, 1, v82
	v_add_u32_e32 v3, 0, v96
	v_lshl_add_u32 v99, v0, 1, 0
	v_or_b32_e32 v67, 3, v82
	v_mul_u32_u24_e32 v0, 48, v87
	s_or_b32 s0, s10, s1
	v_add_u32_e32 v94, v66, v41
	v_add_u32_e32 v100, v48, v41
	v_cmp_gt_u32_e64 s[50:51], v67, v87
	v_lshl_add_u64 v[68:69], s[8:9], 0, v[42:43]
	v_add_u32_e32 v102, s0, v78
	v_add_u32_e32 v103, s0, v44
	v_add_u32_e32 v105, v3, v0
	v_add_u32_e32 v106, v45, v40
	v_lshrrev_b32_e32 v174, 1, v96
	v_sub_u32_e32 v175, v105, v174
	v_add_u32_e32 v174, v66, v174
	s_branch .LBB0_351
.LBB0_350:
	s_waitcnt lgkmcnt(0)
	s_barrier
	s_add_i32 s54, s54, 1
	v_pk_mul_f32 v[10:11], v[10:11], v[220:221]
	v_pk_mul_f32 v[8:9], v[8:9], v[218:219]
	s_add_i32 s53, s53, 32
	s_cmpk_eq_i32 s53, 0x100
	v_mfma_f32_16x16x16_bf16 v[8:11], v[236:237], v[238:239], v[8:11]
	ds_read_b128 v[40:43], v106 offset:23552
	s_waitcnt lgkmcnt(0)
	v_pk_mul_f32 v[0:1], v[42:43], v[42:43]
	v_pk_mul_f32 v[44:45], v[40:41], v[40:41]
	s_nop 0
	v_pk_mov_b32 v[46:47], v[44:45], v[0:1] op_sel:[1,0]
	v_mov_b32_e32 v45, v1
	v_pk_add_f32 v[0:1], v[46:47], v[44:45]
	s_waitcnt vmcnt(12)
	v_lshlrev_b32_e32 v44, 16, v80
	v_add_f32_e32 v0, v0, v1
	ds_bpermute_b32 v1, v119, v0
	v_and_b32_e32 v45, 0xffff0000, v80
	s_waitcnt lgkmcnt(0)
	v_add_f32_e32 v0, v0, v1
	ds_bpermute_b32 v1, v120, v0
	s_waitcnt lgkmcnt(0)
	v_add_f32_e32 v0, v0, v1
	ds_bpermute_b32 v1, v121, v0
	s_waitcnt lgkmcnt(0)
	v_add_f32_e32 v0, v0, v1
	ds_bpermute_b32 v1, v122, v0
	s_waitcnt lgkmcnt(0)
	v_add_f32_e32 v0, v0, v1
	ds_bpermute_b32 v1, v123, v0
	s_waitcnt lgkmcnt(0)
	v_add_f32_e32 v0, v0, v1
	v_fmamk_f32 v0, v0, 0x3c000000, v178
	v_cmp_gt_f32_e32 vcc, s34, v0
	v_mul_f32_e32 v1, 0x4b800000, v0
	s_nop 0
	v_cndmask_b32_e32 v0, v0, v1, vcc
	v_rsq_f32_e32 v0, v0
	s_nop 0
	v_mul_f32_e32 v1, 0x45800000, v0
	v_cndmask_b32_e32 v0, v0, v1, vcc
	v_pk_mul_f32 v[40:41], v[40:41], v[0:1] op_sel_hi:[1,0]
	v_pk_mul_f32 v[0:1], v[42:43], v[0:1] op_sel_hi:[1,0]
	v_pk_mul_f32 v[40:41], v[4:5], v[40:41]
	v_pk_mul_f32 v[0:1], v[6:7], v[0:1]
	v_lshlrev_b32_e32 v42, 16, v81
	v_and_b32_e32 v43, 0xffff0000, v81
	v_pk_mul_f32 v[40:41], v[40:41], v[44:45]
	v_pk_mul_f32 v[0:1], v[0:1], v[42:43]
	v_cvt_pk_bf16_f32 v40, v40, v41
	v_cvt_pk_bf16_f32 v41, v0, v1
	v_lshlrev_b64 v[0:1], 11, v[78:79]
	v_lshl_add_u64 v[0:1], v[64:65], 0, v[0:1]
	global_store_dwordx2 v[0:1], v[40:41], off
	s_cbranch_scc1 .LBB0_415

.LBB0_363:
	s_waitcnt lgkmcnt(0)
	s_barrier
	ds_read_b128 v[40:43], v93 offset:4352
	ds_read_b128 v[118:121], v93
	ds_read2_b64 v[122:125], v100 offset1:4
	ds_read_b128 v[126:129], v93 offset:4416
	ds_read_b128 v[130:133], v93 offset:64
	ds_read_b128 v[134:137], v93 offset:4480
	v_cvt_pk_bf16_f32 v44, v36, v37
	v_cvt_pk_bf16_f32 v45, v38, v39
	v_cvt_pk_bf16_f32 v46, v32, v33
	s_waitcnt lgkmcnt(4)
	v_mfma_f32_16x16x32_bf16 v[40:43], v[40:43], v[118:121], 0
	v_cvt_pk_bf16_f32 v47, v34, v35
	ds_read2_b64 v[138:141], v100 offset0:8 offset1:12
	ds_read_b128 v[142:145], v93 offset:128
	ds_read_b128 v[158:161], v93 offset:4544
	v_cvt_pk_bf16_f32 v118, v28, v29
	s_waitcnt lgkmcnt(4)
	v_mfma_f32_16x16x32_bf16 v[40:43], v[126:129], v[130:133], v[40:43]
	ds_read_b128 v[130:133], v93 offset:192
	v_cvt_pk_bf16_f32 v119, v30, v31
	v_cvt_pk_bf16_f32 v120, v24, v25
	v_cvt_pk_bf16_f32 v121, v26, v27
	s_waitcnt lgkmcnt(2)
	v_mfma_f32_16x16x32_bf16 v[40:43], v[134:137], v[142:145], v[40:43]
	v_cvt_pk_bf16_f32 v126, v20, v21
	v_cvt_pk_bf16_f32 v127, v22, v23
	v_cvt_pk_bf16_f32 v128, v16, v17
	v_mfma_f32_16x16x32_bf16 v[44:47], v[44:47], v[122:125], 0
	v_cvt_pk_bf16_f32 v129, v18, v19
	ds_read2_b64 v[134:137], v100 offset0:16 offset1:20
	ds_read2_b64 v[122:125], v100 offset0:24 offset1:28
	s_waitcnt lgkmcnt(2)
	v_mfma_f32_16x16x32_bf16 v[40:43], v[158:161], v[130:133], v[40:43]
	v_cvt_pk_bf16_f32 v130, v12, v13
	v_cvt_pk_bf16_f32 v131, v14, v15
	v_cvt_pk_bf16_f32 v132, v8, v9
	v_mfma_f32_16x16x32_bf16 v[44:47], v[118:121], v[138:141], v[44:47]
	v_cvt_pk_bf16_f32 v133, v10, v11
	s_nop 2
	v_cndmask_b32_e64 v0, v40, 0, s[44:45]
	v_cndmask_b32_e64 v1, 0, v41, s[46:47]
	ds_read_b64 v[40:41], v94 offset:14848
	s_waitcnt lgkmcnt(2)
	v_mfma_f32_16x16x32_bf16 v[44:47], v[126:129], v[134:137], v[44:47]
	v_cndmask_b32_e64 v3, v42, 0, s[48:49]
	v_cndmask_b32_e64 v48, v43, 0, s[50:51]
	v_mov_b32_e32 v42, v2
	v_mov_b32_e32 v43, v2
	s_waitcnt lgkmcnt(1)
	v_mfma_f32_16x16x32_bf16 v[44:47], v[130:133], v[122:125], v[44:47]
	v_cvt_pk_bf16_f32 v0, v0, v1
	v_cvt_pk_bf16_f32 v1, v3, v48
	v_mov_b32_e32 v3, v2
	v_add_u32_e32 v118, v66, v96
	s_waitcnt lgkmcnt(0)
	v_mfma_f32_16x16x32_bf16 v[40:43], v[40:43], v[0:3], v[44:47]
	s_nop 2
	v_mov_b32_e32 v44, 0
	s_nop 3
	ds_write_b128 v95, v[40:43] offset:23552
	ds_read_b64 v[238:239], v174 offset:14848
	ds_read_b64 v[222:223], v175 offset:8704
	ds_read_b128 v[190:193], v97 offset:20992
	ds_read_b64 v[224:225], v175 offset:9472
	ds_read_b128 v[194:197], v97 offset:21056
	ds_read_b64 v[226:227], v175 offset:10240
	ds_read_b128 v[198:201], v97 offset:21120
	ds_read_b64 v[228:229], v175 offset:11008
	ds_read_b128 v[202:205], v97 offset:21184
	ds_read_b64 v[230:231], v175 offset:11776
	ds_read_b128 v[206:209], v97 offset:21248
	ds_read_b64 v[232:233], v175 offset:12544
	ds_read_b128 v[210:213], v97 offset:21312
	s_waitcnt lgkmcnt(10)
	v_pk_mul_f32 v[38:39], v[38:39], v[192:193]
	v_pk_mul_f32 v[36:37], v[36:37], v[190:191]
	s_nop 1
	v_mfma_f32_16x16x16_bf16 v[36:39], v[222:223], v[238:239], v[36:39]
	ds_read_b64 v[234:235], v175 offset:13312
	ds_read_b128 v[214:217], v97 offset:21376
	s_waitcnt lgkmcnt(10)
	v_pk_mul_f32 v[34:35], v[34:35], v[196:197]
	v_pk_mul_f32 v[32:33], v[32:33], v[194:195]
	s_nop 1
	v_mfma_f32_16x16x16_bf16 v[32:35], v[224:225], v[238:239], v[32:35]
	ds_read_b64 v[236:237], v175 offset:14080
	ds_read_b128 v[218:221], v97 offset:21440
	s_waitcnt lgkmcnt(10)
	v_pk_mul_f32 v[30:31], v[30:31], v[200:201]
	v_pk_mul_f32 v[28:29], v[28:29], v[198:199]
	s_nop 1
	v_mfma_f32_16x16x16_bf16 v[28:31], v[226:227], v[238:239], v[28:31]
	s_waitcnt lgkmcnt(8)
	v_pk_mul_f32 v[26:27], v[26:27], v[204:205]
	v_pk_mul_f32 v[24:25], v[24:25], v[202:203]
	s_nop 1
	v_mfma_f32_16x16x16_bf16 v[24:27], v[228:229], v[238:239], v[24:27]
	s_waitcnt lgkmcnt(6)
	v_pk_mul_f32 v[22:23], v[22:23], v[208:209]
	v_pk_mul_f32 v[20:21], v[20:21], v[206:207]
	s_nop 1
	v_mfma_f32_16x16x16_bf16 v[20:23], v[230:231], v[238:239], v[20:23]
	s_waitcnt lgkmcnt(4)
	v_pk_mul_f32 v[18:19], v[18:19], v[212:213]
	v_pk_mul_f32 v[16:17], v[16:17], v[210:211]
	s_nop 1
	v_mfma_f32_16x16x16_bf16 v[16:19], v[232:233], v[238:239], v[16:19]
	s_waitcnt lgkmcnt(2)
	v_pk_mul_f32 v[14:15], v[14:15], v[216:217]
	v_pk_mul_f32 v[12:13], v[12:13], v[214:215]
	s_nop 1
	v_mfma_f32_16x16x16_bf16 v[12:15], v[234:235], v[238:239], v[12:15]
	v_mov_b32_e32 v1, 0
	s_waitcnt lgkmcnt(0)
	s_barrier
	v_cmp_lt_i32_e32 vcc, v182, v181
	v_pk_mul_f32 v[10:11], v[10:11], v[220:221]
	v_pk_mul_f32 v[8:9], v[8:9], v[218:219]
	v_cndmask_b32_e32 v3, v179, v182, vcc
	v_lshlrev_b32_e32 v119, 2, v3
	v_mfma_f32_16x16x16_bf16 v[8:11], v[236:237], v[238:239], v[8:11]
	ds_read_b128 v[40:43], v106 offset:23552
	v_cmp_lt_i32_e32 vcc, v183, v181
	s_waitcnt lgkmcnt(0)
	v_pk_mul_f32 v[44:45], v[42:43], v[42:43]
	v_pk_mul_f32 v[46:47], v[40:41], v[40:41]
	s_nop 0
	v_pk_mov_b32 v[48:49], v[46:47], v[44:45] op_sel:[1,0]
	v_mov_b32_e32 v47, v45
	v_pk_add_f32 v[44:45], v[48:49], v[46:47]
	s_nop 0
	v_add_f32_e32 v0, v44, v45
	ds_bpermute_b32 v3, v119, v0
	s_waitcnt vmcnt(12)
	v_lshlrev_b32_e32 v44, 16, v80
	v_and_b32_e32 v45, 0xffff0000, v80
	s_waitcnt lgkmcnt(0)
	v_add_f32_e32 v0, v0, v3
	v_cndmask_b32_e32 v3, v179, v183, vcc
	v_lshlrev_b32_e32 v120, 2, v3
	ds_bpermute_b32 v3, v120, v0
	v_cmp_lt_i32_e32 vcc, v184, v181
	s_waitcnt lgkmcnt(0)
	v_add_f32_e32 v0, v0, v3
	v_cndmask_b32_e32 v3, v179, v184, vcc
	v_lshlrev_b32_e32 v121, 2, v3
	ds_bpermute_b32 v3, v121, v0
	v_cmp_lt_i32_e32 vcc, v185, v181
	s_waitcnt lgkmcnt(0)
	v_add_f32_e32 v0, v0, v3
	v_cndmask_b32_e32 v3, v179, v185, vcc
	v_lshlrev_b32_e32 v122, 2, v3
	ds_bpermute_b32 v3, v122, v0
	v_cmp_lt_i32_e32 vcc, v186, v181
	s_waitcnt lgkmcnt(0)
	v_add_f32_e32 v0, v0, v3
	v_cndmask_b32_e32 v3, v179, v186, vcc
	v_lshlrev_b32_e32 v123, 2, v3
	ds_bpermute_b32 v3, v123, v0
	s_waitcnt lgkmcnt(0)
	v_add_f32_e32 v0, v0, v3
	v_fmamk_f32 v0, v0, 0x3c000000, v178
	v_cmp_gt_f32_e32 vcc, s34, v0
	v_mul_f32_e32 v3, 0x4b800000, v0
	s_nop 0
	v_cndmask_b32_e32 v0, v0, v3, vcc
	v_rsq_f32_e32 v0, v0
	s_nop 0
	v_mul_f32_e32 v3, 0x45800000, v0
	v_cndmask_b32_e32 v0, v0, v3, vcc
	v_pk_mul_f32 v[40:41], v[40:41], v[0:1] op_sel_hi:[1,0]
	v_pk_mul_f32 v[42:43], v[42:43], v[0:1] op_sel_hi:[1,0]
	v_pk_mul_f32 v[40:41], v[4:5], v[40:41]
	v_pk_mul_f32 v[42:43], v[6:7], v[42:43]
	v_pk_mul_f32 v[40:41], v[40:41], v[44:45]
	v_lshlrev_b32_e32 v44, 16, v81
	v_and_b32_e32 v45, 0xffff0000, v81
	v_pk_mul_f32 v[42:43], v[42:43], v[44:45]
	v_cvt_pk_bf16_f32 v40, v40, v41
	v_cvt_pk_bf16_f32 v41, v42, v43
	v_lshlrev_b64 v[42:43], 11, v[78:79]
	v_lshl_add_u64 v[42:43], v[64:65], 0, v[42:43]
	v_add_u32_e32 v78, 16, v78
	global_store_dwordx2 v[42:43], v[40:41], off
	v_mad_i64_i32 v[40:41], s[0:1], v78, s30, v[68:69]
	global_load_dwordx2 v[80:81], v[40:41], off offset:1024
	v_sub_f32_e32 v0, 1.0, v58
	v_max_f32_e32 v112, 0xda24260, v0
	v_sub_f32_e32 v0, 1.0, v59
	v_max_f32_e32 v114, 0xda24260, v0
	v_sub_f32_e32 v0, 1.0, v62
	v_max_f32_e32 v115, 0xda24260, v0
	v_sub_f32_e32 v0, 1.0, v63
	v_max_f32_e32 v116, 0xda24260, v0
	v_lshlrev_b32_e32 v74, 16, v170
	v_lshlrev_b32_e32 v75, 16, v171
	v_lshlrev_b32_e32 v76, 16, v172
	v_lshlrev_b32_e32 v77, 16, v173
	v_cmp_gt_f32_e32 vcc, s34, v112
	s_nop 1
	v_cndmask_b32_e64 v0, 0, 32, vcc
	v_ldexp_f32 v0, v112, v0
	v_log_f32_e32 v0, v0
	s_nop 0
	v_mul_f32_e32 v3, 0x3f317217, v0
	v_fma_f32 v3, v0, s97, -v3
	v_fmac_f32_e32 v3, 0x3377d1cf, v0
	v_fmac_f32_e32 v3, 0x3f317217, v0
	v_cmp_lt_f32_e64 s[0:1], |v0|, s35
	s_nop 1
	v_cndmask_b32_e64 v0, v0, v3, s[0:1]
	v_cndmask_b32_e32 v3, 0, v188, vcc
	v_sub_f32_e32 v0, v0, v3
	v_cmp_gt_f32_e32 vcc, s34, v114
	v_add_f32_e32 v47, 0, v0
	s_nop 0
	v_cndmask_b32_e64 v0, 0, 32, vcc
	v_ldexp_f32 v0, v114, v0
	v_log_f32_e32 v0, v0
	s_nop 0
	v_mul_f32_e32 v3, 0x3f317217, v0
	v_fma_f32 v3, v0, s97, -v3
	v_fmac_f32_e32 v3, 0x3377d1cf, v0
	v_fmac_f32_e32 v3, 0x3f317217, v0
	v_cmp_lt_f32_e64 s[0:1], |v0|, s35
	s_nop 1
	v_cndmask_b32_e64 v0, v0, v3, s[0:1]
	v_cndmask_b32_e32 v3, 0, v188, vcc
	v_sub_f32_e32 v0, v0, v3
	v_cmp_gt_f32_e32 vcc, s34, v115
	v_add_f32_e32 v3, v0, v47
	s_nop 0
	v_cndmask_b32_e64 v0, 0, 32, vcc
	v_ldexp_f32 v0, v115, v0
	v_log_f32_e32 v0, v0
	s_nop 0
	v_mul_f32_e32 v40, 0x3f317217, v0
	v_fma_f32 v40, v0, s97, -v40
	v_fmac_f32_e32 v40, 0x3377d1cf, v0
	v_fmac_f32_e32 v40, 0x3f317217, v0
	v_cmp_lt_f32_e64 s[0:1], |v0|, s35
	s_nop 1
	v_cndmask_b32_e64 v0, v0, v40, s[0:1]
	v_cndmask_b32_e32 v40, 0, v188, vcc
	v_sub_f32_e32 v0, v0, v40
	v_cmp_gt_f32_e32 vcc, s34, v116
	v_add_f32_e32 v46, v0, v3
	s_nop 0
	v_cndmask_b32_e64 v0, 0, 32, vcc
	v_ldexp_f32 v0, v116, v0
	v_log_f32_e32 v0, v0
	s_nop 0
	v_mul_f32_e32 v40, 0x3f317217, v0
	v_fma_f32 v40, v0, s97, -v40
	v_fmac_f32_e32 v40, 0x3377d1cf, v0
	v_fmac_f32_e32 v40, 0x3f317217, v0
	v_cmp_lt_f32_e64 s[0:1], |v0|, s35
	s_nop 1
	v_cndmask_b32_e64 v0, v0, v40, s[0:1]
	v_cndmask_b32_e32 v40, 0, v188, vcc
	v_sub_f32_e32 v0, v0, v40
	v_add_f32_e32 v41, v0, v46
	ds_write_b32 v88, v41 offset:21504
	s_waitcnt lgkmcnt(0)
	s_barrier
	ds_read2st64_b32 v[42:43], v91 offset0:84 offset1:86
	ds_read2st64_b32 v[44:45], v91 offset0:88 offset1:90
	s_and_saveexec_b64 s[0:1], s[40:41]
	s_cbranch_execz .LBB0_389
	v_cmp_lt_i32_e32 vcc, 1, v83
	s_mov_b64 s[10:11], 0
	s_and_saveexec_b64 s[12:13], vcc
	s_xor_b64 s[12:13], exec, s[12:13]
	s_cbranch_execz .LBB0_413
	v_cmp_eq_u32_e32 vcc, 2, v83
	s_mov_b64 s[10:11], -1
	s_and_saveexec_b64 s[14:15], vcc
	s_cbranch_execz .LBB0_385
	s_waitcnt lgkmcnt(1)
	v_add_f32_e32 v1, v42, v43
	s_xor_b64 s[10:11], exec, -1

.LBB0_393:
	s_waitcnt lgkmcnt(0)
	s_barrier
	ds_read_b128 v[40:43], v93 offset:4352
	ds_read_b128 v[124:127], v93
	ds_read2_b64 v[128:131], v100 offset1:4
	ds_read_b128 v[132:135], v93 offset:4416
	ds_read_b128 v[136:139], v93 offset:64
	ds_read_b128 v[140:143], v93 offset:4480
	v_cvt_pk_bf16_f32 v44, v36, v37
	v_cvt_pk_bf16_f32 v45, v38, v39
	v_cvt_pk_bf16_f32 v46, v32, v33
	s_waitcnt lgkmcnt(4)
	v_mfma_f32_16x16x32_bf16 v[40:43], v[40:43], v[124:127], 0
	v_cvt_pk_bf16_f32 v47, v34, v35
	ds_read2_b64 v[144:147], v100 offset0:8 offset1:12
	ds_read_b128 v[158:161], v93 offset:128
	ds_read_b128 v[162:165], v93 offset:4544
	v_cvt_pk_bf16_f32 v124, v28, v29
	s_waitcnt lgkmcnt(4)
	v_mfma_f32_16x16x32_bf16 v[40:43], v[132:135], v[136:139], v[40:43]
	ds_read_b128 v[136:139], v93 offset:192
	v_cvt_pk_bf16_f32 v125, v30, v31
	v_cvt_pk_bf16_f32 v126, v24, v25
	v_cvt_pk_bf16_f32 v127, v26, v27
	s_waitcnt lgkmcnt(2)
	v_mfma_f32_16x16x32_bf16 v[40:43], v[140:143], v[158:161], v[40:43]
	v_cvt_pk_bf16_f32 v132, v20, v21
	v_cvt_pk_bf16_f32 v133, v22, v23
	v_cvt_pk_bf16_f32 v134, v16, v17
	v_mfma_f32_16x16x32_bf16 v[44:47], v[44:47], v[128:131], 0
	v_cvt_pk_bf16_f32 v135, v18, v19
	ds_read2_b64 v[140:143], v100 offset0:16 offset1:20
	ds_read2_b64 v[128:131], v100 offset0:24 offset1:28
	s_waitcnt lgkmcnt(2)
	v_mfma_f32_16x16x32_bf16 v[40:43], v[162:165], v[136:139], v[40:43]
	v_cvt_pk_bf16_f32 v136, v12, v13
	v_cvt_pk_bf16_f32 v137, v14, v15
	v_cvt_pk_bf16_f32 v138, v8, v9
	v_mfma_f32_16x16x32_bf16 v[44:47], v[124:127], v[144:147], v[44:47]
	v_cvt_pk_bf16_f32 v139, v10, v11
	s_nop 2
	v_cndmask_b32_e64 v0, v40, 0, s[44:45]
	v_cndmask_b32_e64 v1, 0, v41, s[46:47]
	ds_read_b64 v[40:41], v94 offset:14848
	s_waitcnt lgkmcnt(2)
	v_mfma_f32_16x16x32_bf16 v[44:47], v[132:135], v[140:143], v[44:47]
	v_cndmask_b32_e64 v3, v42, 0, s[48:49]
	v_cndmask_b32_e64 v48, v43, 0, s[50:51]
	v_mov_b32_e32 v42, v2
	v_mov_b32_e32 v43, v2
	s_waitcnt lgkmcnt(1)
	v_mfma_f32_16x16x32_bf16 v[44:47], v[136:139], v[128:131], v[44:47]
	v_cvt_pk_bf16_f32 v0, v0, v1
	v_cvt_pk_bf16_f32 v1, v3, v48
	v_mov_b32_e32 v3, v2
	s_waitcnt lgkmcnt(0)
	s_nop 0
	v_mfma_f32_16x16x32_bf16 v[40:43], v[40:43], v[0:3], v[44:47]
	s_nop 2
	v_mov_b32_e32 v44, 0
	s_nop 3
	ds_write_b128 v95, v[40:43] offset:23552
	ds_read_b64 v[238:239], v174 offset:14848
	ds_read_b64 v[222:223], v175 offset:8704
	ds_read_b128 v[190:193], v97 offset:20992
	ds_read_b64 v[224:225], v175 offset:9472
	ds_read_b128 v[194:197], v97 offset:21056
	ds_read_b64 v[226:227], v175 offset:10240
	ds_read_b128 v[198:201], v97 offset:21120
	ds_read_b64 v[228:229], v175 offset:11008
	ds_read_b128 v[202:205], v97 offset:21184
	ds_read_b64 v[230:231], v175 offset:11776
	ds_read_b128 v[206:209], v97 offset:21248
	ds_read_b64 v[232:233], v175 offset:12544
	ds_read_b128 v[210:213], v97 offset:21312
	s_waitcnt lgkmcnt(10)
	v_pk_mul_f32 v[38:39], v[38:39], v[192:193]
	v_pk_mul_f32 v[36:37], v[36:37], v[190:191]
	s_nop 1
	v_mfma_f32_16x16x16_bf16 v[36:39], v[222:223], v[238:239], v[36:39]
	ds_read_b64 v[234:235], v175 offset:13312
	ds_read_b128 v[214:217], v97 offset:21376
	s_waitcnt lgkmcnt(10)
	v_pk_mul_f32 v[34:35], v[34:35], v[196:197]
	v_pk_mul_f32 v[32:33], v[32:33], v[194:195]
	s_nop 1
	v_mfma_f32_16x16x16_bf16 v[32:35], v[224:225], v[238:239], v[32:35]
	ds_read_b64 v[236:237], v175 offset:14080
	ds_read_b128 v[218:221], v97 offset:21440
	s_waitcnt lgkmcnt(10)
	v_pk_mul_f32 v[30:31], v[30:31], v[200:201]
	v_pk_mul_f32 v[28:29], v[28:29], v[198:199]
	s_nop 1
	v_mfma_f32_16x16x16_bf16 v[28:31], v[226:227], v[238:239], v[28:31]
	s_waitcnt lgkmcnt(8)
	v_pk_mul_f32 v[26:27], v[26:27], v[204:205]
	v_pk_mul_f32 v[24:25], v[24:25], v[202:203]
	s_nop 1
	v_mfma_f32_16x16x16_bf16 v[24:27], v[228:229], v[238:239], v[24:27]
	s_waitcnt lgkmcnt(6)
	v_pk_mul_f32 v[22:23], v[22:23], v[208:209]
	v_pk_mul_f32 v[20:21], v[20:21], v[206:207]
	s_nop 1
	v_mfma_f32_16x16x16_bf16 v[20:23], v[230:231], v[238:239], v[20:23]
	s_waitcnt lgkmcnt(4)
	v_pk_mul_f32 v[18:19], v[18:19], v[212:213]
	v_pk_mul_f32 v[16:17], v[16:17], v[210:211]
	s_nop 1
	v_mfma_f32_16x16x16_bf16 v[16:19], v[232:233], v[238:239], v[16:19]
	s_waitcnt lgkmcnt(2)
	v_pk_mul_f32 v[14:15], v[14:15], v[216:217]
	v_pk_mul_f32 v[12:13], v[12:13], v[214:215]
	s_nop 1
	v_mfma_f32_16x16x16_bf16 v[12:15], v[234:235], v[238:239], v[12:15]
	s_branch .LBB0_350
